# grid barrier reworked: L1 invalidate issued at arrival (overlaps arrival atomic and the XCD leader's L2 write-back), per-XCD invalidate-done counter, leaders poll the top counter directly; same releas
# speedup vs baseline: 1.1194x; 1.0336x over previous
.LBB0_451:
	ds_read_b32 v0, v157 offset:4
	v_readlane_b32 s18, v244, 44
	v_readlane_b32 s19, v244, 45
	s_waitcnt lgkmcnt(0)
	v_readfirstlane_b32 s20, v3
	v_readfirstlane_b32 s21, v2
	v_add_u32_e32 v0, 1, v0
	s_nop 1
	v_readfirstlane_b32 s22, v0
	ds_write_b32 v157, v0 offset:4
	global_atomic_add v4, v1, v158, s[18:19] sc0
	buffer_inv sc1
	s_mul_i32 s23, s22, s20
	s_waitcnt vmcnt(1)
	v_readfirstlane_b32 s3, v4
	s_add_i32 s3, s3, 1
	s_cmp_eq_u32 s3, s23
	s_cbranch_scc1 .Lxb_lead
	v_readlane_b32 s6, v244, 46
	v_readlane_b32 s7, v244, 47
	s_mov_b32 s3, 0
	s_waitcnt vmcnt(0)
	global_atomic_add v1, v158, s[18:19] offset:128
	s_nop 1
.Lxb_w1:
	global_load_dword v2, v1, s[6:7] sc1
	s_add_i32 s3, s3, 1
	s_waitcnt vmcnt(0)
	v_readfirstlane_b32 s24, v2
	s_cmp_ge_u32 s24, s22
	s_cbranch_scc1 .LBB0_19
	s_bitcmp1_b32 s3, 16
	s_cbranch_scc0 .Lxb_w1
	s_branch .LBB0_19
.Lxb_lead:
	buffer_wbl2 sc1
	s_sub_i32 s23, s23, s22
	s_mov_b32 s3, 0
	s_waitcnt vmcnt(0)
.Lxb_w2:
	global_load_dword v2, v1, s[18:19] offset:128 sc1
	s_add_i32 s3, s3, 1
	s_waitcnt vmcnt(0)
	v_readfirstlane_b32 s24, v2
	s_cmp_ge_u32 s24, s23
	s_cbranch_scc1 .Lxb_top
	s_bitcmp1_b32 s3, 16
	s_cbranch_scc0 .Lxb_w2
.Lxb_top:
	v_readlane_b32 s6, v244, 48
	v_readlane_b32 s7, v244, 49
	s_mul_i32 s23, s22, s21
	s_mov_b32 s3, 0
	s_nop 2
	global_atomic_add v1, v158, s[6:7]
.Lxb_w3:
	global_load_dword v2, v1, s[6:7] sc1
	s_add_i32 s3, s3, 1
	s_waitcnt vmcnt(0)
	v_readfirstlane_b32 s24, v2
	s_cmp_ge_u32 s24, s23
	s_cbranch_scc1 .Lxb_rel
	s_bitcmp1_b32 s3, 16
	s_cbranch_scc0 .Lxb_w3
.Lxb_rel:
	v_readlane_b32 s6, v244, 46
	v_readlane_b32 s7, v244, 47
	s_nop 4
	global_atomic_add v1, v158, s[6:7]
	s_branch .LBB0_19
